# speedup vs baseline: 1.0257x; 1.0018x over previous
; DEVI int opq_tid() { int t = threadIdx.x; asm volatile("" : "+v"(t)); return t; }
; #define WAIT_V0() asm volatile("s_waitcnt vmcnt(0)" ::: "memory")
; template <int EPI>
; DEVI void gemm_tile(const u16* __restrict__ Ab, long lda, const u16* __restrict__ Bb, long ldb, int K, const EpiArgs& e,
;                     bool have0 = false, const u16* __restrict__ nA = nullptr, const u16* __restrict__ nB = nullptr) {
;     ...
;   const int tid = opq_tid(), wid = tid >> 6, lane = tid & 63, wr = wid >> 2, wc = wid & 3, fr = lane & 15, fq = lane >> 4;
;   int sR0, sC0; stage_rc(wid * 1024 + lane * 16, sR0, sC0);
;   const int toffA = sR0 * (int)lda + sC0, toffB = sR0 * (int)ldb + sC0;
;   const int a_base = lds_byte(wr * 128 + fr, fq * 8), b_base = TILE_B + lds_byte(wc * 64 + fr, fq * 8);
;     ...
;   f32x4 acc[8][4];
; #pragma unroll
;   for (int m = 0; m < 8; ++m)
; #pragma unroll
;     for (int n = 0; n < 4; ++n) acc[m][n] = f32x4{0.f, 0.f, 0.f, 0.f};
;   const int nt = K / BK;
;   if (!have0) GLDS_STAGE(0, 0);
;   WAIT_V0(); __syncthreads();
.LBB0_147:
	s_xor_b64 s[16:17], s[2:3], -1
	s_mul_hi_i32 s2, s14, 0x2e8ba2e9
	s_lshr_b32 s3, s2, 31
	s_ashr_i32 s2, s2, 5
	s_add_i32 s2, s2, s3
	s_mul_i32 s3, s2, 0xb0
	s_sub_i32 s3, s14, s3
	s_lshl_b32 s6, s2, 3
	s_sext_i32_i16 s2, s3
	s_bfe_u32 s2, s2, 0x3001c
	v_mov_b32_e32 v0, v167
	s_add_i32 s7, s3, s2
	s_sext_i32_i16 s20, s7
	v_ashrrev_i32_e32 v2, 6, v0
	v_lshlrev_b32_e32 v4, 4, v0
	v_and_b32_e32 v5, 32, v0
	s_and_b32 s7, s7, 0xfff8
	v_lshlrev_b32_e32 v7, 5, v2
	v_bitop3_b32 v4, v4, v5, 48 bitop3:0x6c
	s_sub_i32 s3, s3, s7
	v_lshlrev_b32_e32 v6, 3, v2
	v_bfe_u32 v3, v0, 2, 4
	v_lshrrev_b32_e32 v4, 1, v4
	v_and_b32_e32 v5, 32, v7
	s_sext_i32_i16 s3, s3
	v_and_or_b32 v6, v6, s68, v3
	v_or_b32_e32 v7, v4, v5
	s_lshr_b32 s2, s20, 3
	s_add_i32 s6, s6, s3
	v_lshl_or_b32 v6, v6, 10, v7
	s_ashr_i32 s7, s6, 31
	s_bfe_i64 s[2:3], s[2:3], 0x100000
	v_lshlrev_b32_e32 v140, 10, v2
	v_ashrrev_i32_e32 v7, 31, v6
	s_lshl_b64 s[14:15], s[6:7], 19
	s_lshl_b64 s[2:3], s[2:3], 19
	s_andn2_b64 vcc, exec, s[16:17]
	v_lshlrev_b64 v[130:131], 1, v[6:7]
	v_add_u32_e32 v145, 0x8000, v140
	v_add_u32_e32 v144, 0x2000, v140
	v_add_u32_e32 v143, 0xa000, v140
	v_add_u32_e32 v142, 0x4000, v140
	v_add_u32_e32 v141, 0xc000, v140
	v_add_u32_e32 v139, 0x6000, v140
	v_add_u32_e32 v138, 0xe000, v140
	s_cbranch_vccnz .LBB0_149
	s_add_u32 s16, s67, s14
	s_addc_u32 s17, s70, s15
	s_add_u32 s22, s41, s2
	v_readfirstlane_b32 s7, v140
	s_addc_u32 s23, s42, s3
	v_lshl_add_u64 v[6:7], s[16:17], 0, v[130:131]
	s_mov_b32 m0, s7
	v_readfirstlane_b32 s7, v145
	v_lshl_add_u64 v[8:9], s[22:23], 0, v[130:131]
	global_load_lds_dwordx4 v[6:7], off
	s_mov_b32 m0, s7
	s_mov_b64 s[16:17], 0x20000
	v_readfirstlane_b32 s7, v144
	global_load_lds_dwordx4 v[8:9], off
	v_lshl_add_u64 v[10:11], v[6:7], 0, s[16:17]
	s_mov_b32 m0, s7
	v_readfirstlane_b32 s7, v143
	global_load_lds_dwordx4 v[10:11], off
	v_lshl_add_u64 v[10:11], v[8:9], 0, s[16:17]
	s_mov_b32 m0, s7
	v_readfirstlane_b32 s7, v142
	global_load_lds_dwordx4 v[10:11], off
	v_lshl_add_u64 v[10:11], v[6:7], 0, s[96:97]
	s_mov_b32 m0, s7
	v_readfirstlane_b32 s7, v141
	global_load_lds_dwordx4 v[10:11], off
	v_lshl_add_u64 v[10:11], v[8:9], 0, s[96:97]
	s_mov_b32 m0, s7
	s_mov_b64 s[16:17], 0x60000
	v_readfirstlane_b32 s7, v139
	global_load_lds_dwordx4 v[10:11], off
	v_lshl_add_u64 v[6:7], v[6:7], 0, s[16:17]
	s_mov_b32 m0, s7
	v_readfirstlane_b32 s7, v138
	global_load_lds_dwordx4 v[6:7], off
	v_lshl_add_u64 v[6:7], v[8:9], 0, s[16:17]
	s_mov_b32 m0, s7
	s_nop 0
	global_load_lds_dwordx4 v[6:7], off
	s_waitcnt vmcnt(0)
.LBB0_149:
	v_lshrrev_b32_e32 v137, 2, v0
	v_and_b32_e32 v6, 15, v0
	v_ashrrev_i32_e32 v7, 1, v0
	v_and_b32_e32 v8, 48, v0
	v_lshlrev_b32_e32 v0, 2, v0
	v_and_b32_e32 v9, 32, v0
	v_and_b32_e32 v0, 3, v2
	v_lshlrev_b32_e32 v2, 13, v2
	v_and_b32_e32 v2, 0xffffc000, v2
	v_lshlrev_b32_e32 v3, 10, v3
	v_or3_b32 v2, v4, v2, v3
	s_ashr_i32 s7, s20, 3
	v_add_u32_e32 v2, v2, v5
	v_ashrrev_i32_e32 v3, 31, v2
	s_add_u32 s14, s34, s14
	v_lshlrev_b64 v[2:3], 1, v[2:3]
	s_addc_u32 s15, s35, s15
	v_lshl_add_u64 v[132:133], s[14:15], 0, v[2:3]
	v_readlane_b32 s14, v255, 20
	v_readlane_b32 s15, v255, 21
	s_add_u32 s2, s14, s2
	v_and_b32_e32 v7, 0xffffff80, v7
	s_waitcnt vmcnt(16)
	s_addc_u32 s3, s15, s3
	v_or_b32_e32 v136, v7, v6
	v_lshlrev_b32_e32 v6, 6, v6
	v_lshl_add_u64 v[134:135], s[2:3], 0, v[2:3]
	v_mov_b32_e32 v2, 0
	v_lshlrev_b32_e32 v146, 7, v7
	v_bitop3_b32 v147, v6, v9, v8 bitop3:0x36
	v_lshlrev_b32_e32 v148, 13, v0
	s_mov_b32 s2, 0
	s_mov_b64 s[14:15], 0
	v_mov_b32_e32 v3, v2
	v_mov_b32_e32 v4, v2
	v_mov_b32_e32 v5, v2
	v_mov_b32_e32 v6, v2
	v_mov_b32_e32 v7, v2
	v_mov_b32_e32 v8, v2
	v_mov_b32_e32 v9, v2
	v_mov_b32_e32 v10, v2
	v_mov_b32_e32 v11, v2
	v_mov_b32_e32 v12, v2
	v_mov_b32_e32 v13, v2
	v_mov_b32_e32 v14, v2
	v_mov_b32_e32 v15, v2
	v_mov_b32_e32 v16, v2
	v_mov_b32_e32 v17, v2
	v_mov_b32_e32 v18, v2
	v_mov_b32_e32 v19, v2
	v_mov_b32_e32 v20, v2
	v_mov_b32_e32 v21, v2
	v_mov_b32_e32 v22, v2
	v_mov_b32_e32 v23, v2
	v_mov_b32_e32 v24, v2
	v_mov_b32_e32 v25, v2
	v_mov_b32_e32 v26, v2
	v_mov_b32_e32 v27, v2
	v_mov_b32_e32 v28, v2
	v_mov_b32_e32 v29, v2
	v_mov_b32_e32 v30, v2
	v_mov_b32_e32 v31, v2
	v_mov_b32_e32 v32, v2
	v_mov_b32_e32 v33, v2
	v_mov_b32_e32 v34, v2
	v_mov_b32_e32 v35, v2
	v_mov_b32_e32 v36, v2
	v_mov_b32_e32 v37, v2
	v_mov_b32_e32 v38, v2
	v_mov_b32_e32 v39, v2
	v_mov_b32_e32 v40, v2
	v_mov_b32_e32 v41, v2
	v_mov_b32_e32 v42, v2
	v_mov_b32_e32 v43, v2
	v_mov_b32_e32 v44, v2
	v_mov_b32_e32 v45, v2
	v_mov_b32_e32 v46, v2
	v_mov_b32_e32 v47, v2
	v_mov_b32_e32 v48, v2
	v_mov_b32_e32 v49, v2
	v_mov_b32_e32 v50, v2
	v_mov_b32_e32 v51, v2
	v_mov_b32_e32 v52, v2
	v_mov_b32_e32 v53, v2
	v_mov_b32_e32 v54, v2
	v_mov_b32_e32 v55, v2
	v_mov_b32_e32 v56, v2
	v_mov_b32_e32 v57, v2
	v_mov_b32_e32 v58, v2
	v_mov_b32_e32 v59, v2
	v_mov_b32_e32 v60, v2
	v_mov_b32_e32 v61, v2
	v_mov_b32_e32 v62, v2
	v_mov_b32_e32 v63, v2
	v_mov_b32_e32 v64, v2
	v_mov_b32_e32 v65, v2
	v_mov_b32_e32 v66, v2
	v_mov_b32_e32 v67, v2
	v_mov_b32_e32 v68, v2
	v_mov_b32_e32 v69, v2
	v_mov_b32_e32 v70, v2
	v_mov_b32_e32 v71, v2
	v_mov_b32_e32 v72, v2
	v_mov_b32_e32 v73, v2
	v_mov_b32_e32 v74, v2
	v_mov_b32_e32 v75, v2
	v_mov_b32_e32 v76, v2
	v_mov_b32_e32 v77, v2
	v_mov_b32_e32 v78, v2
	v_mov_b32_e32 v79, v2
	v_mov_b32_e32 v80, v2
	v_mov_b32_e32 v81, v2
	v_mov_b32_e32 v82, v2
	v_mov_b32_e32 v83, v2
	v_mov_b32_e32 v84, v2
	v_mov_b32_e32 v85, v2
	v_mov_b32_e32 v86, v2
	v_mov_b32_e32 v87, v2
	v_mov_b32_e32 v88, v2
	v_mov_b32_e32 v89, v2
	v_mov_b32_e32 v90, v2
	v_mov_b32_e32 v91, v2
	v_mov_b32_e32 v92, v2
	v_mov_b32_e32 v93, v2
	v_mov_b32_e32 v94, v2
	v_mov_b32_e32 v95, v2
	v_mov_b32_e32 v96, v2
	v_mov_b32_e32 v97, v2
	v_mov_b32_e32 v98, v2
	v_mov_b32_e32 v99, v2
	v_mov_b32_e32 v100, v2
	v_mov_b32_e32 v101, v2
	v_mov_b32_e32 v102, v2
	v_mov_b32_e32 v103, v2
	v_mov_b32_e32 v104, v2
	v_mov_b32_e32 v105, v2
	v_mov_b32_e32 v106, v2
	v_mov_b32_e32 v107, v2
	v_mov_b32_e32 v108, v2
	v_mov_b32_e32 v109, v2
	v_mov_b32_e32 v110, v2
	v_mov_b32_e32 v111, v2
	v_mov_b32_e32 v112, v2
	v_mov_b32_e32 v113, v2
	v_mov_b32_e32 v114, v2
	v_mov_b32_e32 v115, v2
	v_mov_b32_e32 v116, v2
	v_mov_b32_e32 v117, v2
	v_mov_b32_e32 v118, v2
	v_mov_b32_e32 v119, v2
	v_mov_b32_e32 v120, v2
	v_mov_b32_e32 v121, v2
	v_mov_b32_e32 v122, v2
	v_mov_b32_e32 v123, v2
	v_mov_b32_e32 v124, v2
	v_mov_b32_e32 v125, v2
	v_mov_b32_e32 v126, v2
	v_mov_b32_e32 v127, v2
	v_mov_b32_e32 v128, v2
	v_mov_b32_e32 v129, v2
	s_mov_b64 s[20:21], 0xa500080
	s_mov_b64 s[22:23], 0xa520080
	s_mov_b64 s[26:27], 0xa540080
	s_mov_b64 s[30:31], 0xa560080
	s_waitcnt vmcnt(16) lgkmcnt(0)
	s_barrier

; DEVI int opq_tid() { int t = threadIdx.x; asm volatile("" : "+v"(t)); return t; }
; #define WAIT_V0() asm volatile("s_waitcnt vmcnt(0)" ::: "memory")
; template <int EPI>
; DEVI void gemm_tile(const u16* __restrict__ Ab, long lda, const u16* __restrict__ Bb, long ldb, int K, const EpiArgs& e,
;                     bool have0 = false, const u16* __restrict__ nA = nullptr, const u16* __restrict__ nB = nullptr) {
;     ...
;   const int tid = opq_tid(), wid = tid >> 6, lane = tid & 63, wr = wid >> 2, wc = wid & 3, fr = lane & 15, fq = lane >> 4;
;   int sR0, sC0; stage_rc(wid * 1024 + lane * 16, sR0, sC0);
;   const int toffA = sR0 * (int)lda + sC0, toffB = sR0 * (int)ldb + sC0;
;   const int a_base = lds_byte(wr * 128 + fr, fq * 8), b_base = TILE_B + lds_byte(wc * 64 + fr, fq * 8);
;     ...
;   f32x4 acc[8][4];
; #pragma unroll
;   for (int m = 0; m < 8; ++m)
; #pragma unroll
;     for (int n = 0; n < 4; ++n) acc[m][n] = f32x4{0.f, 0.f, 0.f, 0.f};
;   const int nt = K / BK;
;   if (!have0) GLDS_STAGE(0, 0);
;   WAIT_V0(); __syncthreads();
.LBB0_181:
	s_ashr_i32 s10, s14, 31
	s_lshr_b32 s10, s10, 27
	s_add_i32 s10, s14, s10
	s_ashr_i32 s11, s10, 5
	s_and_b32 s10, s10, 0xffe0
	s_sub_i32 s10, s14, s10
	s_lshl_b32 s14, s11, 3
	s_bfe_i32 s11, s10, 0x80000
	s_bfe_u32 s11, s11, 0x3000c
	v_mov_b32_e32 v131, v167
	s_add_i32 s15, s10, s11
	s_mov_b32 s22, 0xfffff0
	v_lshlrev_b32_e32 v0, 4, v131
	v_and_b32_e32 v4, 32, v131
	v_bfe_i32 v3, v131, 3, 25
	v_bfe_u32 v2, v131, 2, 4
	s_bfe_i32 s11, s15, 0x80000
	s_and_b32 s15, s15, 0xf8
	v_and_or_b32 v5, v3, s22, v2
	v_lshrrev_b32_e32 v6, 1, v131
	v_bitop3_b32 v4, v0, v4, 48 bitop3:0x6c
	s_sub_i32 s10, s10, s15
	v_lshrrev_b32_e32 v4, 1, v4
	v_mul_u32_u24_e32 v7, 0xb00, v5
	v_and_b32_e32 v5, 32, v6
	s_sext_i32_i16 s11, s11
	s_sext_i32_i8 s10, s10
	v_or3_b32 v6, v5, v4, v7
	s_xor_b64 s[2:3], s[2:3], -1
	s_add_i32 s10, s14, s10
	s_ashr_i32 s20, s11, 3
	v_and_b32_e32 v143, 0xfffffc00, v0
	v_ashrrev_i32_e32 v7, 31, v6
	s_mul_hi_i32 s15, s10, 0x160000
	s_mul_i32 s21, s10, 0x160000
	s_mul_hi_i32 s14, s20, 0x160000
	s_mul_i32 s20, s20, 0x160000
	s_andn2_b64 vcc, exec, s[2:3]
	v_lshlrev_b64 v[132:133], 1, v[6:7]
	v_add_u32_e32 v145, 0x8000, v143
	v_add_u32_e32 v144, 0x2000, v143
	v_add_u32_e32 v142, 0xa000, v143
	v_add_u32_e32 v141, 0x4000, v143
	v_add_u32_e32 v140, 0xc000, v143
	v_add_u32_e32 v139, 0x6000, v143
	v_add_u32_e32 v138, 0xe000, v143
	s_cbranch_vccnz .LBB0_183
	v_readlane_b32 s2, v253, 12
	v_readlane_b32 s3, v253, 13
	s_add_u32 s2, s2, s21
	s_addc_u32 s3, s3, s15
	s_add_u32 s22, s17, s20
	v_lshl_add_u64 v[6:7], s[2:3], 0, v[132:133]
	v_readfirstlane_b32 s2, v143
	s_addc_u32 s23, s18, s14
	s_mov_b32 m0, s2
	v_readfirstlane_b32 s2, v145
	v_lshl_add_u64 v[8:9], s[22:23], 0, v[132:133]
	global_load_lds_dwordx4 v[6:7], off
	s_mov_b32 m0, s2
	s_mov_b64 s[22:23], 0x58000
	v_readfirstlane_b32 s2, v144
	global_load_lds_dwordx4 v[8:9], off
	v_lshl_add_u64 v[10:11], v[6:7], 0, s[22:23]
	s_mov_b32 m0, s2
	v_readfirstlane_b32 s2, v142
	global_load_lds_dwordx4 v[10:11], off
	v_lshl_add_u64 v[10:11], v[8:9], 0, s[22:23]
	s_mov_b32 m0, s2
	s_mov_b64 s[22:23], 0xb0000
	v_readfirstlane_b32 s2, v141
	global_load_lds_dwordx4 v[10:11], off
	v_lshl_add_u64 v[10:11], v[6:7], 0, s[22:23]
	s_mov_b32 m0, s2
	v_readfirstlane_b32 s2, v140
	global_load_lds_dwordx4 v[10:11], off
	v_lshl_add_u64 v[10:11], v[8:9], 0, s[22:23]
	s_mov_b32 m0, s2
	s_mov_b64 s[22:23], 0x108000
	v_readfirstlane_b32 s2, v139
	global_load_lds_dwordx4 v[10:11], off
	v_lshl_add_u64 v[6:7], v[6:7], 0, s[22:23]
	s_mov_b32 m0, s2
	v_readfirstlane_b32 s2, v138
	global_load_lds_dwordx4 v[6:7], off
	v_lshl_add_u64 v[6:7], v[8:9], 0, s[22:23]
	s_mov_b32 m0, s2
	s_nop 0
	global_load_lds_dwordx4 v[6:7], off
	s_waitcnt vmcnt(0)
.LBB0_183:
	v_lshrrev_b32_e32 v3, 4, v3
	s_mov_b32 s3, 0xb000
	v_mul_lo_u32 v3, v3, s3
	v_or_b32_e32 v3, v4, v3
	v_mul_u32_u24_e32 v2, 0xb00, v2
	s_lshr_b32 s2, s11, 3
	s_ashr_i32 s11, s10, 31
	v_add3_u32 v2, v3, v2, v5
	v_ashrrev_i32_e32 v3, 31, v2
	s_add_u32 s22, s34, s21
	v_ashrrev_i32_e32 v7, 1, v131
	v_lshlrev_b64 v[2:3], 1, v[2:3]
	s_addc_u32 s23, s35, s15
	v_and_b32_e32 v6, 15, v131
	v_bfe_u32 v0, v131, 4, 2
	v_and_b32_e32 v7, 0xffffff80, v7
	v_lshlrev_b32_e32 v9, 2, v131
	v_lshl_add_u64 v[134:135], s[22:23], 0, v[2:3]
	v_readlane_b32 s22, v255, 20
	v_or_b32_e32 v130, v7, v6
	v_lshlrev_b32_e32 v8, 4, v0
	v_lshlrev_b32_e32 v6, 6, v6
	v_and_b32_e32 v9, 32, v9
	v_readlane_b32 s23, v255, 21
	s_add_u32 s20, s22, s20
	v_bitop3_b32 v146, v6, v9, v8 bitop3:0x36
	v_lshlrev_b32_e32 v6, 6, v131
	s_waitcnt vmcnt(32)
	s_addc_u32 s21, s23, s14
	v_and_b32_e32 v6, 0x3c0, v6
	v_lshlrev_b32_e32 v10, 7, v131
	v_lshl_add_u64 v[136:137], s[20:21], 0, v[2:3]
	v_mov_b32_e32 v2, 0
	v_lshlrev_b32_e32 v147, 7, v7
	v_and_b32_e32 v148, 0x6000, v10
	v_bitop3_b32 v149, v6, v9, v8 bitop3:0x36
	s_mov_b64 s[14:15], 0
	s_mov_b32 s3, 0
	v_mov_b32_e32 v3, v2
	v_mov_b32_e32 v4, v2
	v_mov_b32_e32 v5, v2
	v_mov_b32_e32 v6, v2
	v_mov_b32_e32 v7, v2
	v_mov_b32_e32 v8, v2
	v_mov_b32_e32 v9, v2
	v_mov_b32_e32 v10, v2
	v_mov_b32_e32 v11, v2
	v_mov_b32_e32 v12, v2
	v_mov_b32_e32 v13, v2
	v_mov_b32_e32 v14, v2
	v_mov_b32_e32 v15, v2
	v_mov_b32_e32 v16, v2
	v_mov_b32_e32 v17, v2
	v_mov_b32_e32 v18, v2
	v_mov_b32_e32 v19, v2
	v_mov_b32_e32 v20, v2
	v_mov_b32_e32 v21, v2
	v_mov_b32_e32 v22, v2
	v_mov_b32_e32 v23, v2
	v_mov_b32_e32 v24, v2
	v_mov_b32_e32 v25, v2
	v_mov_b32_e32 v26, v2
	v_mov_b32_e32 v27, v2
	v_mov_b32_e32 v28, v2
	v_mov_b32_e32 v29, v2
	v_mov_b32_e32 v30, v2
	v_mov_b32_e32 v31, v2
	v_mov_b32_e32 v32, v2
	v_mov_b32_e32 v33, v2
	v_mov_b32_e32 v34, v2
	v_mov_b32_e32 v35, v2
	v_mov_b32_e32 v36, v2
	v_mov_b32_e32 v37, v2
	v_mov_b32_e32 v38, v2
	v_mov_b32_e32 v39, v2
	v_mov_b32_e32 v40, v2
	v_mov_b32_e32 v41, v2
	v_mov_b32_e32 v42, v2
	v_mov_b32_e32 v43, v2
	v_mov_b32_e32 v44, v2
	v_mov_b32_e32 v45, v2
	v_mov_b32_e32 v46, v2
	v_mov_b32_e32 v47, v2
	v_mov_b32_e32 v48, v2
	v_mov_b32_e32 v49, v2
	v_mov_b32_e32 v50, v2
	v_mov_b32_e32 v51, v2
	v_mov_b32_e32 v52, v2
	v_mov_b32_e32 v53, v2
	v_mov_b32_e32 v54, v2
	v_mov_b32_e32 v55, v2
	v_mov_b32_e32 v56, v2
	v_mov_b32_e32 v57, v2
	v_mov_b32_e32 v58, v2
	v_mov_b32_e32 v59, v2
	v_mov_b32_e32 v60, v2
	v_mov_b32_e32 v61, v2
	v_mov_b32_e32 v62, v2
	v_mov_b32_e32 v63, v2
	v_mov_b32_e32 v64, v2
	v_mov_b32_e32 v65, v2
	v_mov_b32_e32 v66, v2
	v_mov_b32_e32 v67, v2
	v_mov_b32_e32 v68, v2
	v_mov_b32_e32 v69, v2
	v_mov_b32_e32 v70, v2
	v_mov_b32_e32 v71, v2
	v_mov_b32_e32 v72, v2
	v_mov_b32_e32 v73, v2
	v_mov_b32_e32 v74, v2
	v_mov_b32_e32 v75, v2
	v_mov_b32_e32 v76, v2
	v_mov_b32_e32 v77, v2
	v_mov_b32_e32 v78, v2
	v_mov_b32_e32 v79, v2
	v_mov_b32_e32 v80, v2
	v_mov_b32_e32 v81, v2
	v_mov_b32_e32 v82, v2
	v_mov_b32_e32 v83, v2
	v_mov_b32_e32 v84, v2
	v_mov_b32_e32 v85, v2
	v_mov_b32_e32 v86, v2
	v_mov_b32_e32 v87, v2
	v_mov_b32_e32 v88, v2
	v_mov_b32_e32 v89, v2
	v_mov_b32_e32 v90, v2
	v_mov_b32_e32 v91, v2
	v_mov_b32_e32 v92, v2
	v_mov_b32_e32 v93, v2
	v_mov_b32_e32 v94, v2
	v_mov_b32_e32 v95, v2
	v_mov_b32_e32 v96, v2
	v_mov_b32_e32 v97, v2
	v_mov_b32_e32 v98, v2
	v_mov_b32_e32 v99, v2
	v_mov_b32_e32 v100, v2
	v_mov_b32_e32 v101, v2
	v_mov_b32_e32 v102, v2
	v_mov_b32_e32 v103, v2
	v_mov_b32_e32 v104, v2
	v_mov_b32_e32 v105, v2
	v_mov_b32_e32 v106, v2
	v_mov_b32_e32 v107, v2
	v_mov_b32_e32 v108, v2
	v_mov_b32_e32 v109, v2
	v_mov_b32_e32 v110, v2
	v_mov_b32_e32 v111, v2
	v_mov_b32_e32 v112, v2
	v_mov_b32_e32 v113, v2
	v_mov_b32_e32 v114, v2
	v_mov_b32_e32 v115, v2
	v_mov_b32_e32 v116, v2
	v_mov_b32_e32 v117, v2
	v_mov_b32_e32 v118, v2
	v_mov_b32_e32 v119, v2
	v_mov_b32_e32 v120, v2
	v_mov_b32_e32 v121, v2
	v_mov_b32_e32 v122, v2
	v_mov_b32_e32 v123, v2
	v_mov_b32_e32 v124, v2
	v_mov_b32_e32 v125, v2
	v_mov_b32_e32 v126, v2
	v_mov_b32_e32 v127, v2
	v_mov_b32_e32 v128, v2
	v_mov_b32_e32 v129, v2
	s_mov_b64 s[24:25], 0x16500080
	s_mov_b64 s[26:27], 0x16558080
	s_mov_b64 s[30:31], 0x165b0080
	s_mov_b64 vcc, 0x16608080
	s_waitcnt vmcnt(32) lgkmcnt(0)
	s_barrier

; DEVI int opq_tid() { int t = threadIdx.x; asm volatile("" : "+v"(t)); return t; }
; #define WAIT_V0() asm volatile("s_waitcnt vmcnt(0)" ::: "memory")
; template <int EPI>
; DEVI void gemm_tile(const u16* __restrict__ Ab, long lda, const u16* __restrict__ Bb, long ldb, int K, const EpiArgs& e,
;                     bool have0 = false, const u16* __restrict__ nA = nullptr, const u16* __restrict__ nB = nullptr) {
;     ...
;   const int tid = opq_tid(), wid = tid >> 6, lane = tid & 63, wr = wid >> 2, wc = wid & 3, fr = lane & 15, fq = lane >> 4;
;   int sR0, sC0; stage_rc(wid * 1024 + lane * 16, sR0, sC0);
;   const int toffA = sR0 * (int)lda + sC0, toffB = sR0 * (int)ldb + sC0;
;   const int a_base = lds_byte(wr * 128 + fr, fq * 8), b_base = TILE_B + lds_byte(wc * 64 + fr, fq * 8);
;     ...
;   f32x4 acc[8][4];
; #pragma unroll
;   for (int m = 0; m < 8; ++m)
; #pragma unroll
;     for (int n = 0; n < 4; ++n) acc[m][n] = f32x4{0.f, 0.f, 0.f, 0.f};
;   const int nt = K / BK;
;   if (!have0) GLDS_STAGE(0, 0);
;   WAIT_V0(); __syncthreads();
.LBB0_1367:
	s_xor_b64 s[20:21], s[2:3], -1
	s_mul_hi_i32 s2, s18, 0x2e8ba2e9
	s_lshr_b32 s3, s2, 31
	s_ashr_i32 s2, s2, 5
	s_add_i32 s2, s2, s3
	s_mul_i32 s3, s2, 0xb0
	s_sub_i32 s3, s18, s3
	s_lshl_b32 s8, s2, 3
	s_sext_i32_i16 s2, s3
	s_bfe_u32 s2, s2, 0x3001c
	v_mov_b32_e32 v0, v167
	s_add_i32 s9, s3, s2
	s_sext_i32_i16 s26, s9
	v_ashrrev_i32_e32 v2, 6, v0
	v_lshlrev_b32_e32 v4, 4, v0
	v_and_b32_e32 v5, 32, v0
	s_and_b32 s9, s9, 0xfff8
	v_lshlrev_b32_e32 v7, 5, v2
	v_bitop3_b32 v4, v4, v5, 48 bitop3:0x6c
	s_sub_i32 s3, s3, s9
	v_lshlrev_b32_e32 v6, 3, v2
	v_bfe_u32 v3, v0, 2, 4
	v_lshrrev_b32_e32 v4, 1, v4
	v_and_b32_e32 v5, 32, v7
	s_sext_i32_i16 s3, s3
	v_and_or_b32 v6, v6, s68, v3
	v_or_b32_e32 v7, v4, v5
	s_lshr_b32 s2, s26, 3
	s_add_i32 s8, s8, s3
	v_lshl_or_b32 v6, v6, 10, v7
	s_ashr_i32 s9, s8, 31
	s_bfe_i64 s[2:3], s[2:3], 0x100000
	v_lshlrev_b32_e32 v140, 10, v2
	v_ashrrev_i32_e32 v7, 31, v6
	s_lshl_b64 s[18:19], s[8:9], 19
	s_lshl_b64 s[2:3], s[2:3], 19
	s_andn2_b64 vcc, exec, s[20:21]
	v_lshlrev_b64 v[130:131], 1, v[6:7]
	v_add_u32_e32 v145, 0x8000, v140
	v_add_u32_e32 v144, 0x2000, v140
	v_add_u32_e32 v143, 0xa000, v140
	v_add_u32_e32 v142, 0x4000, v140
	v_add_u32_e32 v141, 0xc000, v140
	v_add_u32_e32 v139, 0x6000, v140
	v_add_u32_e32 v138, 0xe000, v140
	s_cbranch_vccnz .LBB0_1369
	s_add_u32 s20, s67, s18
	s_addc_u32 s21, s70, s19
	s_add_u32 s30, s23, s2
	v_readfirstlane_b32 s9, v140
	s_addc_u32 s31, s24, s3
	v_lshl_add_u64 v[6:7], s[20:21], 0, v[130:131]
	s_mov_b32 m0, s9
	v_readfirstlane_b32 s9, v145
	v_lshl_add_u64 v[8:9], s[30:31], 0, v[130:131]
	global_load_lds_dwordx4 v[6:7], off
	s_mov_b32 m0, s9
	s_mov_b64 s[20:21], 0x20000
	v_readfirstlane_b32 s9, v144
	global_load_lds_dwordx4 v[8:9], off
	v_lshl_add_u64 v[10:11], v[6:7], 0, s[20:21]
	s_mov_b32 m0, s9
	v_readfirstlane_b32 s9, v143
	global_load_lds_dwordx4 v[10:11], off
	v_lshl_add_u64 v[10:11], v[8:9], 0, s[20:21]
	s_mov_b32 m0, s9
	v_readfirstlane_b32 s9, v142
	global_load_lds_dwordx4 v[10:11], off
	v_lshl_add_u64 v[10:11], v[6:7], 0, s[96:97]
	s_mov_b32 m0, s9
	v_readfirstlane_b32 s9, v141
	global_load_lds_dwordx4 v[10:11], off
	v_lshl_add_u64 v[10:11], v[8:9], 0, s[96:97]
	s_mov_b32 m0, s9
	s_mov_b64 s[20:21], 0x60000
	v_readfirstlane_b32 s9, v139
	global_load_lds_dwordx4 v[10:11], off
	v_lshl_add_u64 v[6:7], v[6:7], 0, s[20:21]
	s_mov_b32 m0, s9
	v_readfirstlane_b32 s9, v138
	global_load_lds_dwordx4 v[6:7], off
	v_lshl_add_u64 v[6:7], v[8:9], 0, s[20:21]
	s_mov_b32 m0, s9
	s_nop 0
	global_load_lds_dwordx4 v[6:7], off
	s_waitcnt vmcnt(0)
.LBB0_1369:
	v_lshrrev_b32_e32 v137, 2, v0
	v_and_b32_e32 v6, 15, v0
	v_ashrrev_i32_e32 v7, 1, v0
	v_and_b32_e32 v8, 48, v0
	v_lshlrev_b32_e32 v0, 2, v0
	v_and_b32_e32 v9, 32, v0
	v_and_b32_e32 v0, 3, v2
	v_lshlrev_b32_e32 v2, 13, v2
	s_ashr_i32 s9, s26, 3
	v_and_b32_e32 v2, 0xffffc000, v2
	v_lshlrev_b32_e32 v3, 10, v3
	v_or3_b32 v2, v4, v2, v3
	s_add_u32 s18, s34, s18
	v_add_u32_e32 v2, v2, v5
	s_addc_u32 s19, s35, s19
	v_readlane_b32 s12, v255, 20
	v_ashrrev_i32_e32 v3, 31, v2
	v_readlane_b32 s13, v255, 21
	s_add_u32 s2, s12, s2
	v_and_b32_e32 v7, 0xffffff80, v7
	s_waitcnt vmcnt(16)
	v_lshlrev_b64 v[2:3], 1, v[2:3]
	s_addc_u32 s3, s13, s3
	v_or_b32_e32 v136, v7, v6
	v_lshlrev_b32_e32 v6, 6, v6
	v_lshl_add_u64 v[132:133], s[18:19], 0, v[2:3]
	v_lshl_add_u64 v[134:135], s[2:3], 0, v[2:3]
	v_mov_b32_e32 v2, 0
	v_lshlrev_b32_e32 v146, 7, v7
	v_bitop3_b32 v147, v6, v9, v8 bitop3:0x36
	v_lshlrev_b32_e32 v148, 13, v0
	s_mov_b32 s2, 0
	s_mov_b64 s[18:19], 0
	v_mov_b32_e32 v3, v2
	v_mov_b32_e32 v4, v2
	v_mov_b32_e32 v5, v2
	v_mov_b32_e32 v6, v2
	v_mov_b32_e32 v7, v2
	v_mov_b32_e32 v8, v2
	v_mov_b32_e32 v9, v2
	v_mov_b32_e32 v10, v2
	v_mov_b32_e32 v11, v2
	v_mov_b32_e32 v12, v2
	v_mov_b32_e32 v13, v2
	v_mov_b32_e32 v14, v2
	v_mov_b32_e32 v15, v2
	v_mov_b32_e32 v16, v2
	v_mov_b32_e32 v17, v2
	v_mov_b32_e32 v18, v2
	v_mov_b32_e32 v19, v2
	v_mov_b32_e32 v20, v2
	v_mov_b32_e32 v21, v2
	v_mov_b32_e32 v22, v2
	v_mov_b32_e32 v23, v2
	v_mov_b32_e32 v24, v2
	v_mov_b32_e32 v25, v2
	v_mov_b32_e32 v26, v2
	v_mov_b32_e32 v27, v2
	v_mov_b32_e32 v28, v2
	v_mov_b32_e32 v29, v2
	v_mov_b32_e32 v30, v2
	v_mov_b32_e32 v31, v2
	v_mov_b32_e32 v32, v2
	v_mov_b32_e32 v33, v2
	v_mov_b32_e32 v34, v2
	v_mov_b32_e32 v35, v2
	v_mov_b32_e32 v36, v2
	v_mov_b32_e32 v37, v2
	v_mov_b32_e32 v38, v2
	v_mov_b32_e32 v39, v2
	v_mov_b32_e32 v40, v2
	v_mov_b32_e32 v41, v2
	v_mov_b32_e32 v42, v2
	v_mov_b32_e32 v43, v2
	v_mov_b32_e32 v44, v2
	v_mov_b32_e32 v45, v2
	v_mov_b32_e32 v46, v2
	v_mov_b32_e32 v47, v2
	v_mov_b32_e32 v48, v2
	v_mov_b32_e32 v49, v2
	v_mov_b32_e32 v50, v2
	v_mov_b32_e32 v51, v2
	v_mov_b32_e32 v52, v2
	v_mov_b32_e32 v53, v2
	v_mov_b32_e32 v54, v2
	v_mov_b32_e32 v55, v2
	v_mov_b32_e32 v56, v2
	v_mov_b32_e32 v57, v2
	v_mov_b32_e32 v58, v2
	v_mov_b32_e32 v59, v2
	v_mov_b32_e32 v60, v2
	v_mov_b32_e32 v61, v2
	v_mov_b32_e32 v62, v2
	v_mov_b32_e32 v63, v2
	v_mov_b32_e32 v64, v2
	v_mov_b32_e32 v65, v2
	v_mov_b32_e32 v66, v2
	v_mov_b32_e32 v67, v2
	v_mov_b32_e32 v68, v2
	v_mov_b32_e32 v69, v2
	v_mov_b32_e32 v70, v2
	v_mov_b32_e32 v71, v2
	v_mov_b32_e32 v72, v2
	v_mov_b32_e32 v73, v2
	v_mov_b32_e32 v74, v2
	v_mov_b32_e32 v75, v2
	v_mov_b32_e32 v76, v2
	v_mov_b32_e32 v77, v2
	v_mov_b32_e32 v78, v2
	v_mov_b32_e32 v79, v2
	v_mov_b32_e32 v80, v2
	v_mov_b32_e32 v81, v2
	v_mov_b32_e32 v82, v2
	v_mov_b32_e32 v83, v2
	v_mov_b32_e32 v84, v2
	v_mov_b32_e32 v85, v2
	v_mov_b32_e32 v86, v2
	v_mov_b32_e32 v87, v2
	v_mov_b32_e32 v88, v2
	v_mov_b32_e32 v89, v2
	v_mov_b32_e32 v90, v2
	v_mov_b32_e32 v91, v2
	v_mov_b32_e32 v92, v2
	v_mov_b32_e32 v93, v2
	v_mov_b32_e32 v94, v2
	v_mov_b32_e32 v95, v2
	v_mov_b32_e32 v96, v2
	v_mov_b32_e32 v97, v2
	v_mov_b32_e32 v98, v2
	v_mov_b32_e32 v99, v2
	v_mov_b32_e32 v100, v2
	v_mov_b32_e32 v101, v2
	v_mov_b32_e32 v102, v2
	v_mov_b32_e32 v103, v2
	v_mov_b32_e32 v104, v2
	v_mov_b32_e32 v105, v2
	v_mov_b32_e32 v106, v2
	v_mov_b32_e32 v107, v2
	v_mov_b32_e32 v108, v2
	v_mov_b32_e32 v109, v2
	v_mov_b32_e32 v110, v2
	v_mov_b32_e32 v111, v2
	v_mov_b32_e32 v112, v2
	v_mov_b32_e32 v113, v2
	v_mov_b32_e32 v114, v2
	v_mov_b32_e32 v115, v2
	v_mov_b32_e32 v116, v2
	v_mov_b32_e32 v117, v2
	v_mov_b32_e32 v118, v2
	v_mov_b32_e32 v119, v2
	v_mov_b32_e32 v120, v2
	v_mov_b32_e32 v121, v2
	v_mov_b32_e32 v122, v2
	v_mov_b32_e32 v123, v2
	v_mov_b32_e32 v124, v2
	v_mov_b32_e32 v125, v2
	v_mov_b32_e32 v126, v2
	v_mov_b32_e32 v127, v2
	v_mov_b32_e32 v128, v2
	v_mov_b32_e32 v129, v2
	s_mov_b64 s[12:13], 0xa500080
	s_mov_b64 s[14:15], 0xa520080
	s_mov_b64 s[26:27], 0xa540080
	s_mov_b64 s[30:31], 0xa560080
	s_waitcnt vmcnt(16) lgkmcnt(0)
	s_barrier

; DEVI int opq_tid() { int t = threadIdx.x; asm volatile("" : "+v"(t)); return t; }
; #define WAIT_V0() asm volatile("s_waitcnt vmcnt(0)" ::: "memory")
; template <int EPI>
; DEVI void gemm_tile(const u16* __restrict__ Ab, long lda, const u16* __restrict__ Bb, long ldb, int K, const EpiArgs& e,
;                     bool have0 = false, const u16* __restrict__ nA = nullptr, const u16* __restrict__ nB = nullptr) {
;   constexpr int BK = 64, TILE_B = 256 * BK * 2, GL = 4, STAGE_B = 2 * TILE_B;
;   const int tid = opq_tid(), wid = tid >> 6, lane = tid & 63, wr = wid >> 2, wc = wid & 3, fr = lane & 15, fq = lane >> 4;
;   int sR0, sC0; stage_rc(wid * 1024 + lane * 16, sR0, sC0);
;   const int toffA = sR0 * (int)lda + sC0, toffB = sR0 * (int)ldb + sC0;
;   const int a_base = lds_byte(wr * 128 + fr, fq * 8), b_base = TILE_B + lds_byte(wc * 64 + fr, fq * 8);
;     ...
;   f32x4 acc[8][4];
; #pragma unroll
;   for (int m = 0; m < 8; ++m)
; #pragma unroll
;     for (int n = 0; n < 4; ++n) acc[m][n] = f32x4{0.f, 0.f, 0.f, 0.f};
;   const int nt = K / BK;
;   if (!have0) GLDS_STAGE(0, 0);
;   WAIT_V0(); __syncthreads();
; DEVI void ffn_gemm2(const Params& P, int l, int which) {
;     ...
;     int pm, pn; tile_rc(t, nM, nN, pm, pn);
;     const int tn = t + gridDim.x; const u16 *nA = nullptr, *nB = nullptr;
;     if (tn < nM * nN) { int qm, qn; tile_rc(tn, nM, nN, qm, qn); nA = hid + (long)qm * 256 * FF; nB = Bt + (long)qn * 256 * FF; }
;     EpiArgs e{}; e.C = out + (long)pm * 256 * 1024 + pn * 256; e.ldc = 1024; e.scale = 1.f; e.bias = nullptr;
;     gemm_tile<EPI_BF16>(hid + (long)pm * 256 * FF, FF, Bt + (long)pn * 256 * FF, FF, FF, e, have, nA, nB);
.LBB0_1401:
	s_ashr_i32 s6, s18, 31
	s_lshr_b32 s6, s6, 27
	s_add_i32 s6, s18, s6
	s_ashr_i32 s7, s6, 5
	s_and_b32 s6, s6, 0xffe0
	s_sub_i32 s6, s18, s6
	s_lshl_b32 s18, s7, 3
	s_bfe_i32 s7, s6, 0x80000
	s_bfe_u32 s7, s7, 0x3000c
	v_mov_b32_e32 v131, v167
	s_add_i32 s19, s6, s7
	s_mov_b32 s26, 0xfffff0
	v_lshlrev_b32_e32 v0, 4, v131
	v_and_b32_e32 v4, 32, v131
	v_bfe_i32 v3, v131, 3, 25
	v_bfe_u32 v2, v131, 2, 4
	s_bfe_i32 s7, s19, 0x80000
	s_and_b32 s19, s19, 0xf8
	v_and_or_b32 v5, v3, s26, v2
	v_lshrrev_b32_e32 v6, 1, v131
	v_bitop3_b32 v4, v0, v4, 48 bitop3:0x6c
	s_sub_i32 s6, s6, s19
	v_lshrrev_b32_e32 v4, 1, v4
	v_mul_u32_u24_e32 v7, 0xb00, v5
	v_and_b32_e32 v5, 32, v6
	s_sext_i32_i16 s7, s7
	s_sext_i32_i8 s6, s6
	v_or3_b32 v6, v5, v4, v7
	s_xor_b64 s[2:3], s[2:3], -1
	s_add_i32 s6, s18, s6
	s_ashr_i32 s24, s7, 3
	v_and_b32_e32 v143, 0xfffffc00, v0
	v_ashrrev_i32_e32 v7, 31, v6
	s_mul_hi_i32 s19, s6, 0x160000
	s_mul_i32 s25, s6, 0x160000
	s_mul_hi_i32 s18, s24, 0x160000
	s_mul_i32 s24, s24, 0x160000
	s_andn2_b64 vcc, exec, s[2:3]
	v_lshlrev_b64 v[132:133], 1, v[6:7]
	v_add_u32_e32 v145, 0x8000, v143
	v_add_u32_e32 v144, 0x2000, v143
	v_add_u32_e32 v142, 0xa000, v143
	v_add_u32_e32 v141, 0x4000, v143
	v_add_u32_e32 v140, 0xc000, v143
	v_add_u32_e32 v139, 0x6000, v143
	v_add_u32_e32 v138, 0xe000, v143
	s_cbranch_vccnz .LBB0_1403
	v_readlane_b32 s2, v253, 12
	v_readlane_b32 s3, v253, 13
	s_add_u32 s2, s2, s25
	s_addc_u32 s3, s3, s19
	s_add_u32 s26, s21, s24
	v_lshl_add_u64 v[6:7], s[2:3], 0, v[132:133]
	v_readfirstlane_b32 s2, v143
	s_addc_u32 s27, s22, s18
	s_mov_b32 m0, s2
	v_readfirstlane_b32 s2, v145
	v_lshl_add_u64 v[8:9], s[26:27], 0, v[132:133]
	global_load_lds_dwordx4 v[6:7], off
	s_mov_b32 m0, s2
	s_mov_b64 s[26:27], 0x58000
	v_readfirstlane_b32 s2, v144
	global_load_lds_dwordx4 v[8:9], off
	v_lshl_add_u64 v[10:11], v[6:7], 0, s[26:27]
	s_mov_b32 m0, s2
	v_readfirstlane_b32 s2, v142
	global_load_lds_dwordx4 v[10:11], off
	v_lshl_add_u64 v[10:11], v[8:9], 0, s[26:27]
	s_mov_b32 m0, s2
	s_mov_b64 s[26:27], 0xb0000
	v_readfirstlane_b32 s2, v141
	global_load_lds_dwordx4 v[10:11], off
	v_lshl_add_u64 v[10:11], v[6:7], 0, s[26:27]
	s_mov_b32 m0, s2
	v_readfirstlane_b32 s2, v140
	global_load_lds_dwordx4 v[10:11], off
	v_lshl_add_u64 v[10:11], v[8:9], 0, s[26:27]
	s_mov_b32 m0, s2
	s_mov_b64 s[26:27], 0x108000
	v_readfirstlane_b32 s2, v139
	global_load_lds_dwordx4 v[10:11], off
	v_lshl_add_u64 v[6:7], v[6:7], 0, s[26:27]
	s_mov_b32 m0, s2
	v_readfirstlane_b32 s2, v138
	global_load_lds_dwordx4 v[6:7], off
	v_lshl_add_u64 v[6:7], v[8:9], 0, s[26:27]
	s_mov_b32 m0, s2
	s_nop 0
	global_load_lds_dwordx4 v[6:7], off
	s_waitcnt vmcnt(0)
.LBB0_1403:
	v_lshrrev_b32_e32 v3, 4, v3
	s_mov_b32 s3, 0xb000
	s_lshr_b32 s2, s7, 3
	s_ashr_i32 s7, s6, 31
	v_mul_lo_u32 v3, v3, s3
	v_ashrrev_i32_e32 v7, 1, v131
	v_or_b32_e32 v3, v4, v3
	v_mul_u32_u24_e32 v2, 0xb00, v2
	s_add_u32 s26, s34, s25
	v_and_b32_e32 v6, 15, v131
	v_bfe_u32 v0, v131, 4, 2
	v_and_b32_e32 v7, 0xffffff80, v7
	v_lshlrev_b32_e32 v9, 2, v131
	v_add3_u32 v2, v3, v2, v5
	s_addc_u32 s27, s35, s19
	v_readlane_b32 s12, v255, 20
	v_or_b32_e32 v130, v7, v6
	v_lshlrev_b32_e32 v8, 4, v0
	v_lshlrev_b32_e32 v6, 6, v6
	v_and_b32_e32 v9, 32, v9
	v_ashrrev_i32_e32 v3, 31, v2
	v_readlane_b32 s13, v255, 21
	s_add_u32 s24, s12, s24
	v_bitop3_b32 v146, v6, v9, v8 bitop3:0x36
	v_lshlrev_b32_e32 v6, 6, v131
	s_waitcnt vmcnt(32)
	v_lshlrev_b64 v[2:3], 1, v[2:3]
	s_addc_u32 s25, s13, s18
	v_and_b32_e32 v6, 0x3c0, v6
	v_lshlrev_b32_e32 v10, 7, v131
	v_lshl_add_u64 v[134:135], s[26:27], 0, v[2:3]
	v_lshl_add_u64 v[136:137], s[24:25], 0, v[2:3]
	v_mov_b32_e32 v2, 0
	v_lshlrev_b32_e32 v147, 7, v7
	v_and_b32_e32 v148, 0x6000, v10
	v_bitop3_b32 v149, v6, v9, v8 bitop3:0x36
	s_mov_b64 s[18:19], 0
	s_mov_b32 s3, 0
	v_mov_b32_e32 v3, v2
	v_mov_b32_e32 v4, v2
	v_mov_b32_e32 v5, v2
	v_mov_b32_e32 v6, v2
	v_mov_b32_e32 v7, v2
	v_mov_b32_e32 v8, v2
	v_mov_b32_e32 v9, v2
	v_mov_b32_e32 v10, v2
	v_mov_b32_e32 v11, v2
	v_mov_b32_e32 v12, v2
	v_mov_b32_e32 v13, v2
	v_mov_b32_e32 v14, v2
	v_mov_b32_e32 v15, v2
	v_mov_b32_e32 v16, v2
	v_mov_b32_e32 v17, v2
	v_mov_b32_e32 v18, v2
	v_mov_b32_e32 v19, v2
	v_mov_b32_e32 v20, v2
	v_mov_b32_e32 v21, v2
	v_mov_b32_e32 v22, v2
	v_mov_b32_e32 v23, v2
	v_mov_b32_e32 v24, v2
	v_mov_b32_e32 v25, v2
	v_mov_b32_e32 v26, v2
	v_mov_b32_e32 v27, v2
	v_mov_b32_e32 v28, v2
	v_mov_b32_e32 v29, v2
	v_mov_b32_e32 v30, v2
	v_mov_b32_e32 v31, v2
	v_mov_b32_e32 v32, v2
	v_mov_b32_e32 v33, v2
	v_mov_b32_e32 v34, v2
	v_mov_b32_e32 v35, v2
	v_mov_b32_e32 v36, v2
	v_mov_b32_e32 v37, v2
	v_mov_b32_e32 v38, v2
	v_mov_b32_e32 v39, v2
	v_mov_b32_e32 v40, v2
	v_mov_b32_e32 v41, v2
	v_mov_b32_e32 v42, v2
	v_mov_b32_e32 v43, v2
	v_mov_b32_e32 v44, v2
	v_mov_b32_e32 v45, v2
	v_mov_b32_e32 v46, v2
	v_mov_b32_e32 v47, v2
	v_mov_b32_e32 v48, v2
	v_mov_b32_e32 v49, v2
	v_mov_b32_e32 v50, v2
	v_mov_b32_e32 v51, v2
	v_mov_b32_e32 v52, v2
	v_mov_b32_e32 v53, v2
	v_mov_b32_e32 v54, v2
	v_mov_b32_e32 v55, v2
	v_mov_b32_e32 v56, v2
	v_mov_b32_e32 v57, v2
	v_mov_b32_e32 v58, v2
	v_mov_b32_e32 v59, v2
	v_mov_b32_e32 v60, v2
	v_mov_b32_e32 v61, v2
	v_mov_b32_e32 v62, v2
	v_mov_b32_e32 v63, v2
	v_mov_b32_e32 v64, v2
	v_mov_b32_e32 v65, v2
	v_mov_b32_e32 v66, v2
	v_mov_b32_e32 v67, v2
	v_mov_b32_e32 v68, v2
	v_mov_b32_e32 v69, v2
	v_mov_b32_e32 v70, v2
	v_mov_b32_e32 v71, v2
	v_mov_b32_e32 v72, v2
	v_mov_b32_e32 v73, v2
	v_mov_b32_e32 v74, v2
	v_mov_b32_e32 v75, v2
	v_mov_b32_e32 v76, v2
	v_mov_b32_e32 v77, v2
	v_mov_b32_e32 v78, v2
	v_mov_b32_e32 v79, v2
	v_mov_b32_e32 v80, v2
	v_mov_b32_e32 v81, v2
	v_mov_b32_e32 v82, v2
	v_mov_b32_e32 v83, v2
	v_mov_b32_e32 v84, v2
	v_mov_b32_e32 v85, v2
	v_mov_b32_e32 v86, v2
	v_mov_b32_e32 v87, v2
	v_mov_b32_e32 v88, v2
	v_mov_b32_e32 v89, v2
	v_mov_b32_e32 v90, v2
	v_mov_b32_e32 v91, v2
	v_mov_b32_e32 v92, v2
	v_mov_b32_e32 v93, v2
	v_mov_b32_e32 v94, v2
	v_mov_b32_e32 v95, v2
	v_mov_b32_e32 v96, v2
	v_mov_b32_e32 v97, v2
	v_mov_b32_e32 v98, v2
	v_mov_b32_e32 v99, v2
	v_mov_b32_e32 v100, v2
	v_mov_b32_e32 v101, v2
	v_mov_b32_e32 v102, v2
	v_mov_b32_e32 v103, v2
	v_mov_b32_e32 v104, v2
	v_mov_b32_e32 v105, v2
	v_mov_b32_e32 v106, v2
	v_mov_b32_e32 v107, v2
	v_mov_b32_e32 v108, v2
	v_mov_b32_e32 v109, v2
	v_mov_b32_e32 v110, v2
	v_mov_b32_e32 v111, v2
	v_mov_b32_e32 v112, v2
	v_mov_b32_e32 v113, v2
	v_mov_b32_e32 v114, v2
	v_mov_b32_e32 v115, v2
	v_mov_b32_e32 v116, v2
	v_mov_b32_e32 v117, v2
	v_mov_b32_e32 v118, v2
	v_mov_b32_e32 v119, v2
	v_mov_b32_e32 v120, v2
	v_mov_b32_e32 v121, v2
	v_mov_b32_e32 v122, v2
	v_mov_b32_e32 v123, v2
	v_mov_b32_e32 v124, v2
	v_mov_b32_e32 v125, v2
	v_mov_b32_e32 v126, v2
	v_mov_b32_e32 v127, v2
	v_mov_b32_e32 v128, v2
	v_mov_b32_e32 v129, v2
	s_mov_b64 s[30:31], 0x16500080
	s_mov_b64 vcc, 0x16558080
	s_mov_b64 s[12:13], 0x165b0080
	s_mov_b64 s[14:15], 0x16608080
	s_waitcnt vmcnt(32) lgkmcnt(0)
	s_barrier
